# write-through (sc1) stores in the GEMM epilogues so the grid barrier's L2 writeback finds little dirty data
# speedup vs baseline: 1.0022x; 1.0022x over previous
.LBB0_157:
	s_cmp_lt_i32 s42, s15
	s_cselect_b64 vcc, -1, 0
	v_mov_b32_e32 v130, 0x3e38aa3b
	v_cndmask_b32_e32 v130, 1.0, v130, vcc
	v_pk_mul_f32 v[128:129], v[130:131], v[128:129] op_sel_hi:[0,1]
	v_pk_mul_f32 v[126:127], v[130:131], v[126:127] op_sel_hi:[0,1]
	v_pk_mul_f32 v[132:133], v[130:131], v[124:125] op_sel_hi:[0,1]
	v_pk_mul_f32 v[124:125], v[130:131], v[122:123] op_sel_hi:[0,1]
	v_cvt_pk_bf16_f32 v122, v126, v127
	v_cvt_pk_bf16_f32 v123, v128, v129
	v_cvt_pk_bf16_f32 v124, v124, v125
	v_cvt_pk_bf16_f32 v125, v132, v133
	v_lshl_add_u64 v[126:127], v[158:159], 1, s[80:81]
	s_and_b64 vcc, exec, s[8:9]
	global_store_dwordx4 v[126:127], v[122:125], off sc1
	s_cbranch_vccnz .LBB0_223
	s_cmp_lt_i32 s16, 2
	s_mov_b64 s[34:35], -1
	s_cbranch_scc1 .LBB0_190
	s_cmp_eq_u32 s16, 2
	v_mov_b32_e32 v122, v118
	s_cbranch_scc0 .LBB0_161
	v_mul_f32_e32 v122, 0x3d372713, v118
	v_mul_f32_e32 v122, v118, v122
	v_fma_f32 v122, v118, v122, v118
	v_mul_f32_e32 v122, 0x3f4c422a, v122
	v_mul_f32_e32 v122, -2.0, v122
	v_mul_f32_e32 v122, 0x3fb8aa3b, v122
	v_exp_f32_e32 v122, v122
	s_nop 0
	v_add_f32_e32 v122, 1.0, v122
	v_rcp_f32_e32 v122, v122
	s_nop 0
	v_mul_f32_e32 v122, v118, v122

.LBB0_223:
	v_mov_b32_e32 v131, v130
	v_mov_b32_e32 v122, v130
	v_mov_b32_e32 v123, v130
	v_pk_mul_f32 v[120:121], v[122:123], v[120:121]
	v_pk_mul_f32 v[118:119], v[130:131], v[118:119]
	v_pk_mul_f32 v[122:123], v[122:123], v[116:117]
	v_pk_mul_f32 v[116:117], v[130:131], v[114:115]
	v_cvt_pk_bf16_f32 v114, v118, v119
	v_cvt_pk_bf16_f32 v115, v120, v121
	v_cvt_pk_bf16_f32 v116, v116, v117
	v_cvt_pk_bf16_f32 v117, v122, v123
	v_lshl_add_u64 v[118:119], v[156:157], 1, s[80:81]
	s_and_b64 vcc, exec, s[8:9]
	global_store_dwordx4 v[118:119], v[114:117], off sc1
	s_cbranch_vccnz .LBB0_289
	s_cmp_lt_i32 s16, 2
	s_mov_b64 s[34:35], -1
	s_cbranch_scc1 .LBB0_256
	s_cmp_eq_u32 s16, 2
	v_mov_b32_e32 v114, v110
	s_cbranch_scc0 .LBB0_227
	v_mul_f32_e32 v114, 0x3d372713, v110
	v_mul_f32_e32 v114, v110, v114
	v_fma_f32 v114, v110, v114, v110
	v_mul_f32_e32 v114, 0x3f4c422a, v114
	v_mul_f32_e32 v114, -2.0, v114
	v_mul_f32_e32 v114, 0x3fb8aa3b, v114
	v_exp_f32_e32 v114, v114
	s_nop 0
	v_add_f32_e32 v114, 1.0, v114
	v_rcp_f32_e32 v114, v114
	s_nop 0
	v_mul_f32_e32 v114, v110, v114

.LBB0_289:
	s_nop 0
	v_mov_b32_e32 v114, v130
	v_mov_b32_e32 v115, v130
	v_pk_mul_f32 v[112:113], v[114:115], v[112:113]
	v_pk_mul_f32 v[110:111], v[130:131], v[110:111]
	v_pk_mul_f32 v[114:115], v[114:115], v[108:109]
	v_pk_mul_f32 v[108:109], v[130:131], v[106:107]
	s_lshl_b64 s[34:35], s[98:99], 5
	v_cvt_pk_bf16_f32 v106, v110, v111
	v_cvt_pk_bf16_f32 v107, v112, v113
	v_cvt_pk_bf16_f32 v108, v108, v109
	v_cvt_pk_bf16_f32 v109, v114, v115
	v_lshl_add_u64 v[110:111], v[126:127], 0, s[34:35]
	s_and_b64 vcc, exec, s[8:9]
	global_store_dwordx4 v[110:111], v[106:109], off sc1
	s_cbranch_vccnz .LBB0_355
	s_cmp_lt_i32 s16, 2
	s_mov_b64 vcc, -1
	s_cbranch_scc1 .LBB0_322
	s_cmp_eq_u32 s16, 2
	v_mov_b32_e32 v106, v102
	s_cbranch_scc0 .LBB0_293
	v_mul_f32_e32 v106, 0x3d372713, v102
	v_mul_f32_e32 v106, v102, v106
	v_fma_f32 v106, v102, v106, v102
	v_mul_f32_e32 v106, 0x3f4c422a, v106
	v_mul_f32_e32 v106, -2.0, v106
	v_mul_f32_e32 v106, 0x3fb8aa3b, v106
	v_exp_f32_e32 v106, v106
	s_nop 0
	v_add_f32_e32 v106, 1.0, v106
	v_rcp_f32_e32 v106, v106
	s_nop 0
	v_mul_f32_e32 v106, v102, v106

.LBB0_355:
	s_nop 0
	v_mov_b32_e32 v106, v130
	v_mov_b32_e32 v107, v130
	s_lshl_b64 vcc, s[98:99], 4
	v_pk_mul_f32 v[104:105], v[106:107], v[104:105]
	v_pk_mul_f32 v[102:103], v[130:131], v[102:103]
	v_pk_mul_f32 v[106:107], v[106:107], v[100:101]
	v_pk_mul_f32 v[100:101], v[130:131], v[98:99]
	v_cvt_pk_bf16_f32 v98, v102, v103
	v_cvt_pk_bf16_f32 v99, v104, v105
	v_cvt_pk_bf16_f32 v100, v100, v101
	v_cvt_pk_bf16_f32 v101, v106, v107
	v_lshl_add_u64 v[102:103], vcc, 1, v[118:119]
	s_and_b64 vcc, exec, s[8:9]
	global_store_dwordx4 v[102:103], v[98:101], off sc1
	s_cbranch_vccnz .LBB0_421
	s_cmp_lt_i32 s16, 2
	s_mov_b64 vcc, -1
	s_cbranch_scc1 .LBB0_388
	s_cmp_eq_u32 s16, 2
	v_mov_b32_e32 v98, v94
	s_cbranch_scc0 .LBB0_359
	v_mul_f32_e32 v98, 0x3d372713, v94
	v_mul_f32_e32 v98, v94, v98
	v_fma_f32 v98, v94, v98, v94
	v_mul_f32_e32 v98, 0x3f4c422a, v98
	v_mul_f32_e32 v98, -2.0, v98
	v_mul_f32_e32 v98, 0x3fb8aa3b, v98
	v_exp_f32_e32 v98, v98
	s_nop 0
	v_add_f32_e32 v98, 1.0, v98
	v_rcp_f32_e32 v98, v98
	s_nop 0
	v_mul_f32_e32 v98, v94, v98

.LBB0_421:
	s_nop 0
	v_mov_b32_e32 v98, v130
	v_mov_b32_e32 v99, v130
	v_pk_mul_f32 v[96:97], v[98:99], v[96:97]
	v_pk_mul_f32 v[94:95], v[130:131], v[94:95]
	v_pk_mul_f32 v[98:99], v[98:99], v[92:93]
	v_pk_mul_f32 v[92:93], v[130:131], v[90:91]
	v_cvt_pk_bf16_f32 v90, v94, v95
	v_cvt_pk_bf16_f32 v91, v96, v97
	v_cvt_pk_bf16_f32 v92, v92, v93
	v_cvt_pk_bf16_f32 v93, v98, v99
	v_lshl_add_u64 v[94:95], v[110:111], 0, s[34:35]
	s_and_b64 vcc, exec, s[8:9]
	global_store_dwordx4 v[94:95], v[90:93], off sc1
	s_cbranch_vccnz .LBB0_487
	s_cmp_lt_i32 s16, 2
	s_mov_b64 vcc, -1
	s_cbranch_scc1 .LBB0_454
	s_cmp_eq_u32 s16, 2
	v_mov_b32_e32 v90, v86
	s_cbranch_scc0 .LBB0_425
	v_mul_f32_e32 v90, 0x3d372713, v86
	v_mul_f32_e32 v90, v86, v90
	v_fma_f32 v90, v86, v90, v86
	v_mul_f32_e32 v90, 0x3f4c422a, v90
	v_mul_f32_e32 v90, -2.0, v90
	v_mul_f32_e32 v90, 0x3fb8aa3b, v90
	v_exp_f32_e32 v90, v90
	s_nop 0
	v_add_f32_e32 v90, 1.0, v90
	v_rcp_f32_e32 v90, v90
	s_nop 0
	v_mul_f32_e32 v90, v86, v90

.LBB0_487:
	s_nop 0
	v_mov_b32_e32 v90, v130
	v_mov_b32_e32 v91, v130
	v_pk_mul_f32 v[88:89], v[90:91], v[88:89]
	v_pk_mul_f32 v[86:87], v[130:131], v[86:87]
	v_pk_mul_f32 v[90:91], v[90:91], v[84:85]
	v_pk_mul_f32 v[84:85], v[130:131], v[82:83]
	v_cvt_pk_bf16_f32 v82, v86, v87
	v_cvt_pk_bf16_f32 v83, v88, v89
	v_cvt_pk_bf16_f32 v84, v84, v85
	v_cvt_pk_bf16_f32 v85, v90, v91
	v_lshl_add_u64 v[86:87], v[102:103], 0, s[34:35]
	s_and_b64 vcc, exec, s[8:9]
	global_store_dwordx4 v[86:87], v[82:85], off sc1
	s_cbranch_vccnz .LBB0_553
	s_cmp_lt_i32 s16, 2
	s_mov_b64 vcc, -1
	s_cbranch_scc1 .LBB0_520
	s_cmp_eq_u32 s16, 2
	v_mov_b32_e32 v82, v78
	s_cbranch_scc0 .LBB0_491
	v_mul_f32_e32 v82, 0x3d372713, v78
	v_mul_f32_e32 v82, v78, v82
	v_fma_f32 v82, v78, v82, v78
	v_mul_f32_e32 v82, 0x3f4c422a, v82
	v_mul_f32_e32 v82, -2.0, v82
	v_mul_f32_e32 v82, 0x3fb8aa3b, v82
	v_exp_f32_e32 v82, v82
	s_nop 0
	v_add_f32_e32 v82, 1.0, v82
	v_rcp_f32_e32 v82, v82
	s_nop 0
	v_mul_f32_e32 v82, v78, v82

.LBB0_553:
	s_nop 0
	v_mov_b32_e32 v82, v130
	v_mov_b32_e32 v83, v130
	v_pk_mul_f32 v[80:81], v[82:83], v[80:81]
	v_pk_mul_f32 v[78:79], v[130:131], v[78:79]
	v_pk_mul_f32 v[82:83], v[82:83], v[76:77]
	v_pk_mul_f32 v[76:77], v[130:131], v[74:75]
	v_cvt_pk_bf16_f32 v74, v78, v79
	v_cvt_pk_bf16_f32 v75, v80, v81
	v_cvt_pk_bf16_f32 v76, v76, v77
	v_cvt_pk_bf16_f32 v77, v82, v83
	v_lshl_add_u64 v[78:79], v[94:95], 0, s[34:35]
	s_and_b64 vcc, exec, s[8:9]
	global_store_dwordx4 v[78:79], v[74:77], off sc1
	s_cbranch_vccnz .LBB0_619
	s_cmp_lt_i32 s16, 2
	s_mov_b64 vcc, -1
	s_cbranch_scc1 .LBB0_586
	s_cmp_eq_u32 s16, 2
	v_mov_b32_e32 v74, v70
	s_cbranch_scc0 .LBB0_557
	v_mul_f32_e32 v74, 0x3d372713, v70
	v_mul_f32_e32 v74, v70, v74
	v_fma_f32 v74, v70, v74, v70
	v_mul_f32_e32 v74, 0x3f4c422a, v74
	v_mul_f32_e32 v74, -2.0, v74
	v_mul_f32_e32 v74, 0x3fb8aa3b, v74
	v_exp_f32_e32 v74, v74
	s_nop 0
	v_add_f32_e32 v74, 1.0, v74
	v_rcp_f32_e32 v74, v74
	s_nop 0
	v_mul_f32_e32 v74, v70, v74

.LBB0_619:
	s_nop 0
	v_mov_b32_e32 v74, v130
	v_mov_b32_e32 v75, v130
	v_pk_mul_f32 v[72:73], v[74:75], v[72:73]
	v_pk_mul_f32 v[70:71], v[130:131], v[70:71]
	v_pk_mul_f32 v[74:75], v[74:75], v[68:69]
	v_pk_mul_f32 v[68:69], v[130:131], v[66:67]
	v_cvt_pk_bf16_f32 v66, v70, v71
	v_cvt_pk_bf16_f32 v67, v72, v73
	v_cvt_pk_bf16_f32 v68, v68, v69
	v_cvt_pk_bf16_f32 v69, v74, v75
	v_lshl_add_u64 v[70:71], v[86:87], 0, s[34:35]
	s_and_b64 vcc, exec, s[8:9]
	global_store_dwordx4 v[70:71], v[66:69], off sc1
	s_cbranch_vccnz .LBB0_685
	s_cmp_lt_i32 s16, 2
	s_mov_b64 vcc, -1
	s_cbranch_scc1 .LBB0_652
	s_cmp_eq_u32 s16, 2
	v_mov_b32_e32 v66, v62
	s_cbranch_scc0 .LBB0_623
	v_mul_f32_e32 v66, 0x3d372713, v62
	v_mul_f32_e32 v66, v62, v66
	v_fma_f32 v66, v62, v66, v62
	v_mul_f32_e32 v66, 0x3f4c422a, v66
	v_mul_f32_e32 v66, -2.0, v66
	v_mul_f32_e32 v66, 0x3fb8aa3b, v66
	v_exp_f32_e32 v66, v66
	s_nop 0
	v_add_f32_e32 v66, 1.0, v66
	v_rcp_f32_e32 v66, v66
	s_nop 0
	v_mul_f32_e32 v66, v62, v66

.LBB0_685:
	s_nop 0
	v_mov_b32_e32 v66, v130
	v_mov_b32_e32 v67, v130
	v_pk_mul_f32 v[62:63], v[130:131], v[62:63]
	v_pk_mul_f32 v[64:65], v[66:67], v[64:65]
	v_pk_mul_f32 v[66:67], v[66:67], v[60:61]
	v_pk_mul_f32 v[60:61], v[130:131], v[58:59]
	v_cvt_pk_bf16_f32 v58, v62, v63
	v_mov_b32_e32 v62, 0xa0
	s_mul_i32 s41, s99, 0xa0
	v_mad_u64_u32 v[62:63], s[50:51], s98, v62, v[78:79]
	v_cvt_pk_bf16_f32 v59, v64, v65
	v_cvt_pk_bf16_f32 v60, v60, v61
	v_cvt_pk_bf16_f32 v61, v66, v67
	v_add_u32_e32 v63, s41, v63
	s_and_b64 vcc, exec, s[8:9]
	global_store_dwordx4 v[62:63], v[58:61], off sc1
	s_cbranch_vccnz .LBB0_751
	s_cmp_lt_i32 s16, 2
	s_mov_b64 vcc, -1
	s_cbranch_scc1 .LBB0_718
	s_cmp_eq_u32 s16, 2
	v_mov_b32_e32 v58, v54
	s_cbranch_scc0 .LBB0_689
	v_mul_f32_e32 v58, 0x3d372713, v54
	v_mul_f32_e32 v58, v54, v58
	v_fma_f32 v58, v54, v58, v54
	v_mul_f32_e32 v58, 0x3f4c422a, v58
	v_mul_f32_e32 v58, -2.0, v58
	v_mul_f32_e32 v58, 0x3fb8aa3b, v58
	v_exp_f32_e32 v58, v58
	s_nop 0
	v_add_f32_e32 v58, 1.0, v58
	v_rcp_f32_e32 v58, v58
	s_nop 0
	v_mul_f32_e32 v58, v54, v58

.LBB0_751:
	s_mul_hi_u32 s42, s98, 0xa0
	v_mov_b32_e32 v58, v130
	v_mov_b32_e32 v59, v130
	s_add_i32 s99, s42, s41
	s_mulk_i32 s98, 0xa0
	v_pk_mul_f32 v[56:57], v[58:59], v[56:57]
	v_pk_mul_f32 v[54:55], v[130:131], v[54:55]
	v_pk_mul_f32 v[58:59], v[58:59], v[52:53]
	v_pk_mul_f32 v[52:53], v[130:131], v[50:51]
	v_cvt_pk_bf16_f32 v50, v54, v55
	v_cvt_pk_bf16_f32 v51, v56, v57
	v_cvt_pk_bf16_f32 v52, v52, v53
	v_cvt_pk_bf16_f32 v53, v58, v59
	v_lshl_add_u64 v[54:55], v[70:71], 0, s[98:99]
	s_and_b64 vcc, exec, s[8:9]
	global_store_dwordx4 v[54:55], v[50:53], off sc1
	s_cbranch_vccnz .LBB0_817
	s_cmp_lt_i32 s16, 2
	s_mov_b64 s[98:99], -1
	s_cbranch_scc1 .LBB0_784
	s_cmp_eq_u32 s16, 2
	v_mov_b32_e32 v50, v46
	s_cbranch_scc0 .LBB0_755
	v_mul_f32_e32 v50, 0x3d372713, v46
	v_mul_f32_e32 v50, v46, v50
	v_fma_f32 v50, v46, v50, v46
	v_mul_f32_e32 v50, 0x3f4c422a, v50
	v_mul_f32_e32 v50, -2.0, v50
	v_mul_f32_e32 v50, 0x3fb8aa3b, v50
	v_exp_f32_e32 v50, v50
	s_nop 0
	v_add_f32_e32 v50, 1.0, v50
	v_rcp_f32_e32 v50, v50
	s_nop 0
	v_mul_f32_e32 v50, v46, v50

.LBB0_817:
	s_nop 0
	v_mov_b32_e32 v50, v130
	v_mov_b32_e32 v51, v130
	v_pk_mul_f32 v[48:49], v[50:51], v[48:49]
	v_pk_mul_f32 v[46:47], v[130:131], v[46:47]
	v_pk_mul_f32 v[50:51], v[50:51], v[44:45]
	v_pk_mul_f32 v[44:45], v[130:131], v[42:43]
	v_cvt_pk_bf16_f32 v42, v46, v47
	v_cvt_pk_bf16_f32 v43, v48, v49
	v_cvt_pk_bf16_f32 v44, v44, v45
	v_cvt_pk_bf16_f32 v45, v50, v51
	v_lshl_add_u64 v[46:47], v[62:63], 0, s[34:35]
	s_and_b64 vcc, exec, s[8:9]
	global_store_dwordx4 v[46:47], v[42:45], off sc1
	s_cbranch_vccnz .LBB0_883
	s_cmp_lt_i32 s16, 2
	s_mov_b64 s[98:99], -1
	s_cbranch_scc1 .LBB0_850
	s_cmp_eq_u32 s16, 2
	v_mov_b32_e32 v42, v38
	s_cbranch_scc0 .LBB0_821
	v_mul_f32_e32 v42, 0x3d372713, v38
	v_mul_f32_e32 v42, v38, v42
	v_fma_f32 v42, v38, v42, v38
	v_mul_f32_e32 v42, 0x3f4c422a, v42
	v_mul_f32_e32 v42, -2.0, v42
	v_mul_f32_e32 v42, 0x3fb8aa3b, v42
	v_exp_f32_e32 v42, v42
	s_nop 0
	v_add_f32_e32 v42, 1.0, v42
	v_rcp_f32_e32 v42, v42
	s_nop 0
	v_mul_f32_e32 v42, v38, v42

.LBB0_883:
	s_nop 0
	v_mov_b32_e32 v42, v130
	v_mov_b32_e32 v43, v130
	v_pk_mul_f32 v[40:41], v[42:43], v[40:41]
	v_pk_mul_f32 v[38:39], v[130:131], v[38:39]
	v_pk_mul_f32 v[42:43], v[42:43], v[36:37]
	v_pk_mul_f32 v[36:37], v[130:131], v[34:35]
	v_cvt_pk_bf16_f32 v34, v38, v39
	v_cvt_pk_bf16_f32 v35, v40, v41
	v_cvt_pk_bf16_f32 v36, v36, v37
	v_cvt_pk_bf16_f32 v37, v42, v43
	v_lshl_add_u64 v[38:39], v[54:55], 0, s[34:35]
	s_and_b64 vcc, exec, s[8:9]
	global_store_dwordx4 v[38:39], v[34:37], off sc1
	s_cbranch_vccnz .LBB0_949
	s_cmp_lt_i32 s16, 2
	s_mov_b64 s[98:99], -1
	s_cbranch_scc1 .LBB0_916
	s_cmp_eq_u32 s16, 2
	v_mov_b32_e32 v34, v30
	s_cbranch_scc0 .LBB0_887
	v_mul_f32_e32 v34, 0x3d372713, v30
	v_mul_f32_e32 v34, v30, v34
	v_fma_f32 v34, v30, v34, v30
	v_mul_f32_e32 v34, 0x3f4c422a, v34
	v_mul_f32_e32 v34, -2.0, v34
	v_mul_f32_e32 v34, 0x3fb8aa3b, v34
	v_exp_f32_e32 v34, v34
	s_nop 0
	v_add_f32_e32 v34, 1.0, v34
	v_rcp_f32_e32 v34, v34
	s_nop 0
	v_mul_f32_e32 v34, v30, v34

.LBB0_949:
	s_nop 0
	v_mov_b32_e32 v34, v130
	v_mov_b32_e32 v35, v130
	v_pk_mul_f32 v[32:33], v[34:35], v[32:33]
	v_pk_mul_f32 v[30:31], v[130:131], v[30:31]
	v_pk_mul_f32 v[34:35], v[34:35], v[28:29]
	v_pk_mul_f32 v[28:29], v[130:131], v[26:27]
	v_cvt_pk_bf16_f32 v26, v30, v31
	v_cvt_pk_bf16_f32 v27, v32, v33
	v_cvt_pk_bf16_f32 v28, v28, v29
	v_cvt_pk_bf16_f32 v29, v34, v35
	v_lshl_add_u64 v[30:31], v[46:47], 0, s[34:35]
	s_and_b64 vcc, exec, s[8:9]
	global_store_dwordx4 v[30:31], v[26:29], off sc1
	s_cbranch_vccnz .LBB0_1015
	s_cmp_lt_i32 s16, 2
	s_mov_b64 s[98:99], -1
	s_cbranch_scc1 .LBB0_982
	s_cmp_eq_u32 s16, 2
	v_mov_b32_e32 v26, v22
	s_cbranch_scc0 .LBB0_953
	v_mul_f32_e32 v26, 0x3d372713, v22
	v_mul_f32_e32 v26, v22, v26
	v_fma_f32 v26, v22, v26, v22
	v_mul_f32_e32 v26, 0x3f4c422a, v26
	v_mul_f32_e32 v26, -2.0, v26
	v_mul_f32_e32 v26, 0x3fb8aa3b, v26
	v_exp_f32_e32 v26, v26
	s_nop 0
	v_add_f32_e32 v26, 1.0, v26
	v_rcp_f32_e32 v26, v26
	s_nop 0
	v_mul_f32_e32 v26, v22, v26

.LBB0_1015:
	s_nop 0
	v_mov_b32_e32 v26, v130
	v_mov_b32_e32 v27, v130
	v_pk_mul_f32 v[24:25], v[26:27], v[24:25]
	v_pk_mul_f32 v[22:23], v[130:131], v[22:23]
	v_pk_mul_f32 v[26:27], v[26:27], v[20:21]
	v_pk_mul_f32 v[20:21], v[130:131], v[18:19]
	v_cvt_pk_bf16_f32 v18, v22, v23
	v_cvt_pk_bf16_f32 v19, v24, v25
	v_cvt_pk_bf16_f32 v20, v20, v21
	v_cvt_pk_bf16_f32 v21, v26, v27
	v_lshl_add_u64 v[22:23], v[38:39], 0, s[34:35]
	s_and_b64 vcc, exec, s[8:9]
	global_store_dwordx4 v[22:23], v[18:21], off sc1
	s_cbranch_vccnz .LBB0_1081
	s_cmp_lt_i32 s16, 2
	s_mov_b64 s[98:99], -1
	s_cbranch_scc1 .LBB0_1048
	s_cmp_eq_u32 s16, 2
	v_mov_b32_e32 v18, v14
	s_cbranch_scc0 .LBB0_1019
	v_mul_f32_e32 v18, 0x3d372713, v14
	v_mul_f32_e32 v18, v14, v18
	v_fma_f32 v18, v14, v18, v14
	v_mul_f32_e32 v18, 0x3f4c422a, v18
	v_mul_f32_e32 v18, -2.0, v18
	v_mul_f32_e32 v18, 0x3fb8aa3b, v18
	v_exp_f32_e32 v18, v18
	s_nop 0
	v_add_f32_e32 v18, 1.0, v18
	v_rcp_f32_e32 v18, v18
	s_nop 0
	v_mul_f32_e32 v18, v14, v18

.LBB0_1081:
	s_nop 0
	v_mov_b32_e32 v18, v130
	v_mov_b32_e32 v19, v130
	v_pk_mul_f32 v[16:17], v[18:19], v[16:17]
	v_pk_mul_f32 v[14:15], v[130:131], v[14:15]
	v_pk_mul_f32 v[18:19], v[18:19], v[12:13]
	v_pk_mul_f32 v[12:13], v[130:131], v[10:11]
	v_cvt_pk_bf16_f32 v10, v14, v15
	v_cvt_pk_bf16_f32 v11, v16, v17
	v_cvt_pk_bf16_f32 v12, v12, v13
	v_cvt_pk_bf16_f32 v13, v18, v19
	v_lshl_add_u64 v[14:15], v[30:31], 0, s[34:35]
	s_and_b64 vcc, exec, s[8:9]
	global_store_dwordx4 v[14:15], v[10:13], off sc1
	s_cbranch_vccnz .LBB0_1147
	s_cmp_lt_i32 s16, 2
	s_mov_b64 s[8:9], -1
	s_cbranch_scc1 .LBB0_1114
	s_cmp_eq_u32 s16, 2
	v_mov_b32_e32 v10, v6
	s_cbranch_scc0 .LBB0_1085
	v_mul_f32_e32 v10, 0x3d372713, v6
	v_mul_f32_e32 v10, v6, v10
	v_fma_f32 v10, v6, v10, v6
	v_mul_f32_e32 v10, 0x3f4c422a, v10
	v_mul_f32_e32 v10, -2.0, v10
	v_mul_f32_e32 v10, 0x3fb8aa3b, v10
	v_exp_f32_e32 v10, v10
	s_nop 0
	v_add_f32_e32 v10, 1.0, v10
	v_rcp_f32_e32 v10, v10
	s_nop 0
	v_mul_f32_e32 v10, v6, v10

.LBB0_1147:
	s_nop 0
	v_mov_b32_e32 v10, v130
	v_mov_b32_e32 v11, v130
	v_pk_mul_f32 v[8:9], v[10:11], v[8:9]
	v_pk_mul_f32 v[6:7], v[130:131], v[6:7]
	v_pk_mul_f32 v[10:11], v[10:11], v[4:5]
	v_pk_mul_f32 v[4:5], v[130:131], v[2:3]
	v_cvt_pk_bf16_f32 v2, v6, v7
	v_cvt_pk_bf16_f32 v3, v8, v9
	v_cvt_pk_bf16_f32 v4, v4, v5
	v_cvt_pk_bf16_f32 v5, v10, v11
	v_lshl_add_u64 v[6:7], v[22:23], 0, s[34:35]
	s_and_b64 vcc, exec, s[6:7]
	s_mov_b64 s[6:7], -1
	global_store_dwordx4 v[6:7], v[2:5], off sc1
	s_cbranch_vccnz .LBB0_66
	v_readlane_b32 s6, v254, 23
	v_readlane_b32 s7, v254, 24
	s_andn2_b64 vcc, exec, s[6:7]
	s_cbranch_vccnz .LBB0_65
	s_barrier
	s_branch .LBB0_65

.LBB0_1174:
	s_lshl_b32 s26, s63, 8
	v_readlane_b32 s27, v254, 29
	s_add_i32 s30, s26, s27
	s_ashr_i32 s26, s30, 31
	s_lshr_b32 s26, s26, 20
	s_add_i32 s26, s30, s26
	s_ashr_i32 s26, s26, 12
	v_lshl_or_b32 v66, s41, 8, v165
	s_mul_hi_i32 s27, s26, 0x6000
	s_mulk_i32 s26, 0x6000
	v_ashrrev_i32_e32 v67, 31, v66
	v_add_u32_e32 v162, s30, v149
	s_add_u32 s26, s90, s26
	v_lshlrev_b64 v[156:157], 2, v[66:67]
	v_ashrrev_i32_e32 v163, 31, v162
	s_addc_u32 s27, s91, s27
	v_lshl_add_u64 v[158:159], s[94:95], 0, v[156:157]
	v_lshlrev_b64 v[160:161], 12, v[162:163]
	v_lshl_add_u64 v[66:67], s[26:27], 0, v[156:157]
	v_lshl_add_u64 v[178:179], v[158:159], 0, v[160:161]
	global_load_dwordx4 v[102:105], v[66:67], off
	global_load_dwordx4 v[74:77], v[66:67], off offset:64
	global_load_dwordx4 v[70:73], v[66:67], off offset:512
	s_nop 0
	global_load_dwordx4 v[66:69], v[66:67], off offset:576
	s_nop 0
	global_load_dwordx4 v[168:171], v[178:179], off
	global_load_dwordx4 v[172:175], v[178:179], off offset:64
	global_load_dwordx4 v[184:187], v[178:179], off offset:512
	global_load_dwordx4 v[188:191], v[178:179], off offset:576
	v_or_b32_e32 v178, 16, v162
	v_ashrrev_i32_e32 v179, 31, v178
	v_lshlrev_b64 v[178:179], 12, v[178:179]
	v_lshl_add_u64 v[204:205], v[158:159], 0, v[178:179]
	global_load_dwordx4 v[192:195], v[204:205], off
	global_load_dwordx4 v[196:199], v[204:205], off offset:64
	global_load_dwordx4 v[200:203], v[204:205], off offset:512
	s_nop 0
	global_load_dwordx4 v[204:207], v[204:205], off offset:576
	s_mov_b64 s[26:27], 0x80000
	s_and_b64 vcc, exec, s[6:7]
	s_waitcnt vmcnt(0)
	v_pk_fma_f32 v[142:143], v[142:143], v[102:103], v[168:169]
	v_lshl_add_u64 v[168:169], s[88:89], 0, v[160:161]
	v_lshl_add_u64 v[168:169], v[168:169], 0, v[156:157]
	v_pk_fma_f32 v[128:129], v[128:129], v[72:73], v[186:187]
	v_pk_fma_f32 v[126:127], v[126:127], v[70:71], v[184:185]
	global_store_dwordx4 v[168:169], v[126:129], off offset:512 sc1
	v_pk_fma_f32 v[124:125], v[124:125], v[68:69], v[190:191]
	v_pk_fma_f32 v[122:123], v[122:123], v[66:67], v[188:189]
	v_lshl_add_u64 v[126:127], s[88:89], 0, v[178:179]
	v_lshl_add_u64 v[126:127], v[126:127], 0, v[156:157]
	v_pk_fma_f32 v[116:117], v[116:117], v[68:69], v[206:207]
	v_pk_fma_f32 v[114:115], v[114:115], v[66:67], v[204:205]
	global_store_dwordx4 v[168:169], v[122:125], off offset:576 sc1
	global_store_dwordx4 v[126:127], v[114:117], off offset:576 sc1
	v_pk_fma_f32 v[144:145], v[144:145], v[104:105], v[170:171]
	v_pk_fma_f32 v[124:125], v[136:137], v[104:105], v[194:195]
	v_pk_fma_f32 v[122:123], v[134:135], v[102:103], v[192:193]
	v_or_b32_e32 v114, 32, v162
	v_pk_fma_f32 v[140:141], v[140:141], v[76:77], v[174:175]
	v_pk_fma_f32 v[138:139], v[138:139], v[74:75], v[172:173]
	global_store_dwordx4 v[126:127], v[122:125], off sc1
	v_pk_fma_f32 v[120:121], v[120:121], v[72:73], v[202:203]
	v_pk_fma_f32 v[118:119], v[118:119], v[70:71], v[200:201]
	v_pk_fma_f32 v[124:125], v[132:133], v[76:77], v[198:199]
	v_pk_fma_f32 v[122:123], v[130:131], v[74:75], v[196:197]
	v_ashrrev_i32_e32 v115, 31, v114
	global_store_dwordx4 v[168:169], v[142:145], off sc1
	global_store_dwordx4 v[168:169], v[138:141], off offset:64 sc1
	global_store_dwordx4 v[126:127], v[122:125], off offset:64 sc1
	global_store_dwordx4 v[126:127], v[118:121], off offset:512 sc1
	v_lshlrev_b64 v[168:169], 12, v[114:115]
	v_or_b32_e32 v130, 48, v162
	v_lshl_add_u64 v[126:127], v[158:159], 0, v[168:169]
	v_ashrrev_i32_e32 v131, 31, v130
	global_load_dwordx4 v[114:117], v[126:127], off
	global_load_dwordx4 v[118:121], v[126:127], off offset:64
	global_load_dwordx4 v[122:125], v[126:127], off offset:512
	s_nop 0
	global_load_dwordx4 v[126:129], v[126:127], off offset:576
	v_lshlrev_b64 v[162:163], 12, v[130:131]
	v_lshl_add_u64 v[142:143], v[158:159], 0, v[162:163]
	global_load_dwordx4 v[130:133], v[142:143], off
	global_load_dwordx4 v[134:137], v[142:143], off offset:64
	global_load_dwordx4 v[138:141], v[142:143], off offset:512
	s_nop 0
	global_load_dwordx4 v[142:145], v[142:143], off offset:576
	s_waitcnt vmcnt(7)
	v_pk_fma_f32 v[110:111], v[110:111], v[102:103], v[114:115]
	v_lshl_add_u64 v[114:115], s[88:89], 0, v[168:169]
	v_lshl_add_u64 v[114:115], v[114:115], 0, v[156:157]
	s_waitcnt vmcnt(5)
	v_pk_fma_f32 v[92:93], v[92:93], v[72:73], v[124:125]
	v_pk_fma_f32 v[90:91], v[90:91], v[70:71], v[122:123]
	global_store_dwordx4 v[114:115], v[90:93], off offset:512 sc1
	s_waitcnt vmcnt(5)
	v_pk_fma_f32 v[88:89], v[88:89], v[68:69], v[128:129]
	v_pk_fma_f32 v[86:87], v[86:87], v[66:67], v[126:127]
	v_lshl_add_u64 v[90:91], s[88:89], 0, v[162:163]
	global_store_dwordx4 v[114:115], v[86:89], off offset:576 sc1
	v_lshl_add_u64 v[90:91], v[90:91], 0, v[156:157]
	v_pk_fma_f32 v[112:113], v[112:113], v[104:105], v[116:117]
	s_waitcnt vmcnt(5)
	v_pk_fma_f32 v[88:89], v[100:101], v[104:105], v[132:133]
	v_pk_fma_f32 v[86:87], v[98:99], v[102:103], v[130:131]
	v_pk_fma_f32 v[108:109], v[108:109], v[76:77], v[120:121]
	v_pk_fma_f32 v[106:107], v[106:107], v[74:75], v[118:119]
	global_store_dwordx4 v[90:91], v[86:89], off sc1
	s_waitcnt vmcnt(4)
	v_pk_fma_f32 v[84:85], v[84:85], v[72:73], v[140:141]
	v_pk_fma_f32 v[82:83], v[82:83], v[70:71], v[138:139]
	v_pk_fma_f32 v[88:89], v[96:97], v[76:77], v[136:137]
	v_pk_fma_f32 v[86:87], v[94:95], v[74:75], v[134:135]
	s_waitcnt vmcnt(3)
	v_pk_fma_f32 v[80:81], v[80:81], v[68:69], v[144:145]
	v_pk_fma_f32 v[78:79], v[78:79], v[66:67], v[142:143]
	global_store_dwordx4 v[114:115], v[110:113], off sc1
	global_store_dwordx4 v[114:115], v[106:109], off offset:64 sc1
	global_store_dwordx4 v[90:91], v[86:89], off offset:64 sc1
	global_store_dwordx4 v[90:91], v[82:85], off offset:512 sc1
	global_store_dwordx4 v[90:91], v[78:81], off offset:576 sc1
	v_lshl_add_u64 v[114:115], v[160:161], 0, s[26:27]
	v_lshl_add_u64 v[90:91], v[158:159], 0, v[114:115]
	s_mov_b64 s[26:27], 0x90000
	global_load_dwordx4 v[78:81], v[90:91], off
	global_load_dwordx4 v[82:85], v[90:91], off offset:64
	global_load_dwordx4 v[86:89], v[90:91], off offset:512
	s_nop 0
	global_load_dwordx4 v[90:93], v[90:91], off offset:576
	v_lshl_add_u64 v[116:117], v[160:161], 0, s[26:27]
	v_lshl_add_u64 v[110:111], v[158:159], 0, v[116:117]
	global_load_dwordx4 v[94:97], v[110:111], off
	global_load_dwordx4 v[98:101], v[110:111], off offset:64
	global_load_dwordx4 v[106:109], v[110:111], off offset:512
	s_nop 0
	global_load_dwordx4 v[110:113], v[110:111], off offset:576
	s_mov_b64 s[26:27], 0xa0000
	s_waitcnt vmcnt(7)
	v_pk_fma_f32 v[62:63], v[62:63], v[102:103], v[78:79]
	v_lshl_add_u64 v[78:79], s[88:89], 0, v[114:115]
	v_lshl_add_u64 v[78:79], v[78:79], 0, v[156:157]
	s_waitcnt vmcnt(5)
	v_pk_fma_f32 v[48:49], v[48:49], v[72:73], v[88:89]
	v_pk_fma_f32 v[46:47], v[46:47], v[70:71], v[86:87]
	global_store_dwordx4 v[78:79], v[46:49], off offset:512 sc1
	s_waitcnt vmcnt(5)
	v_pk_fma_f32 v[44:45], v[44:45], v[68:69], v[92:93]
	v_pk_fma_f32 v[42:43], v[42:43], v[66:67], v[90:91]
	v_lshl_add_u64 v[46:47], s[88:89], 0, v[116:117]
	global_store_dwordx4 v[78:79], v[42:45], off offset:576 sc1
	v_lshl_add_u64 v[46:47], v[46:47], 0, v[156:157]
	v_pk_fma_f32 v[64:65], v[64:65], v[104:105], v[80:81]
	s_waitcnt vmcnt(5)
	v_pk_fma_f32 v[44:45], v[56:57], v[104:105], v[96:97]
	v_pk_fma_f32 v[42:43], v[54:55], v[102:103], v[94:95]
	v_pk_fma_f32 v[60:61], v[60:61], v[76:77], v[84:85]
	v_pk_fma_f32 v[58:59], v[58:59], v[74:75], v[82:83]
	global_store_dwordx4 v[46:47], v[42:45], off sc1
	s_waitcnt vmcnt(4)
	v_pk_fma_f32 v[40:41], v[40:41], v[72:73], v[108:109]
	v_pk_fma_f32 v[38:39], v[38:39], v[70:71], v[106:107]
	v_pk_fma_f32 v[44:45], v[52:53], v[76:77], v[100:101]
	v_pk_fma_f32 v[42:43], v[50:51], v[74:75], v[98:99]
	s_waitcnt vmcnt(3)
	v_pk_fma_f32 v[36:37], v[36:37], v[68:69], v[112:113]
	v_pk_fma_f32 v[34:35], v[34:35], v[66:67], v[110:111]
	global_store_dwordx4 v[78:79], v[62:65], off sc1
	global_store_dwordx4 v[78:79], v[58:61], off offset:64 sc1
	global_store_dwordx4 v[46:47], v[42:45], off offset:64 sc1
	global_store_dwordx4 v[46:47], v[38:41], off offset:512 sc1
	global_store_dwordx4 v[46:47], v[34:37], off offset:576 sc1
	v_lshl_add_u64 v[78:79], v[160:161], 0, s[26:27]
	s_mov_b64 s[26:27], 0xb0000
	v_lshl_add_u64 v[46:47], v[158:159], 0, v[78:79]
	v_lshl_add_u64 v[80:81], v[160:161], 0, s[26:27]
	global_load_dwordx4 v[34:37], v[46:47], off
	global_load_dwordx4 v[38:41], v[46:47], off offset:64
	global_load_dwordx4 v[42:45], v[46:47], off offset:512
	s_nop 0
	global_load_dwordx4 v[46:49], v[46:47], off offset:576
	v_lshl_add_u64 v[62:63], v[158:159], 0, v[80:81]
	global_load_dwordx4 v[50:53], v[62:63], off
	global_load_dwordx4 v[54:57], v[62:63], off offset:64
	global_load_dwordx4 v[58:61], v[62:63], off offset:512
	s_nop 0
	global_load_dwordx4 v[62:65], v[62:63], off offset:576
	s_mov_b64 s[26:27], -1
	s_waitcnt vmcnt(7)
	v_pk_fma_f32 v[30:31], v[30:31], v[102:103], v[34:35]
	v_lshl_add_u64 v[34:35], s[88:89], 0, v[78:79]
	v_lshl_add_u64 v[34:35], v[34:35], 0, v[156:157]
	s_waitcnt vmcnt(5)
	v_pk_fma_f32 v[20:21], v[20:21], v[72:73], v[44:45]
	v_pk_fma_f32 v[18:19], v[18:19], v[70:71], v[42:43]
	global_store_dwordx4 v[34:35], v[18:21], off offset:512 sc1
	s_waitcnt vmcnt(5)
	v_pk_fma_f32 v[16:17], v[16:17], v[68:69], v[48:49]
	v_pk_fma_f32 v[14:15], v[14:15], v[66:67], v[46:47]
	v_lshl_add_u64 v[18:19], s[88:89], 0, v[80:81]
	v_pk_fma_f32 v[32:33], v[32:33], v[104:105], v[36:37]
	v_pk_fma_f32 v[28:29], v[28:29], v[76:77], v[40:41]
	v_pk_fma_f32 v[26:27], v[26:27], v[74:75], v[38:39]
	global_store_dwordx4 v[34:35], v[14:17], off offset:576 sc1
	v_lshl_add_u64 v[18:19], v[18:19], 0, v[156:157]
	s_waitcnt vmcnt(4)
	v_pk_fma_f32 v[12:13], v[12:13], v[76:77], v[56:57]
	v_pk_fma_f32 v[16:17], v[24:25], v[104:105], v[52:53]
	v_pk_fma_f32 v[14:15], v[22:23], v[102:103], v[50:51]
	v_pk_fma_f32 v[10:11], v[10:11], v[74:75], v[54:55]
	s_waitcnt vmcnt(3)
	v_pk_fma_f32 v[8:9], v[8:9], v[72:73], v[60:61]
	v_pk_fma_f32 v[6:7], v[6:7], v[70:71], v[58:59]
	s_waitcnt vmcnt(2)
	v_pk_fma_f32 v[4:5], v[4:5], v[68:69], v[64:65]
	v_pk_fma_f32 v[2:3], v[2:3], v[66:67], v[62:63]
	global_store_dwordx4 v[34:35], v[30:33], off sc1
	global_store_dwordx4 v[34:35], v[26:29], off offset:64 sc1
	global_store_dwordx4 v[18:19], v[14:17], off sc1
	global_store_dwordx4 v[18:19], v[10:13], off offset:64 sc1
	global_store_dwordx4 v[18:19], v[6:9], off offset:512 sc1
	global_store_dwordx4 v[18:19], v[2:5], off offset:576 sc1
	s_cbranch_vccnz .LBB0_1160
	s_andn2_b64 vcc, exec, s[20:21]
	s_cbranch_vccnz .LBB0_1159
	s_barrier
	s_branch .LBB0_1159
